# on top of v29: forgetting-attention pipelined step accumulates P.V in place in the loop-carried registers (16 MFMAs retargeted), skipping the 16 x v_mov_b64 copy-back and s_nop 8 every step; one copy
# speedup vs baseline: 1.0064x; 1.0064x over previous
.LBB0_887:
	s_andn2_b64 vcc, exec, s[4:5]
	s_cbranch_vccnz .LBB0_889
	v_add_u32_e32 v246, s33, v202
	v_add_u32_e32 v246, 0x18a00, v246
	s_nop 6
	v_add_u32_e32 v0, s58, v197
	v_add_u32_e32 v247, s58, v195
	ds_read_b128 v[66:69], v247
	ds_read_b128 v[70:73], v247 offset:4096
	v_add_u32_e32 v248, s58, v198
	ds_read_b128 v[74:77], v248
	ds_read_b128 v[78:81], v248 offset:4096
	v_add_u32_e32 v249, s58, v199
	ds_read_b128 v[82:85], v249
	ds_read_b128 v[86:89], v249 offset:4096
	v_add_u32_e32 v250, s58, v200
	ds_read_b128 v[90:93], v250
	ds_read_b128 v[94:97], v250 offset:4096
	ds_read_b128 v[34:37], v246 offset:256
	ds_read_b128 v[50:53], v246 offset:384
	ds_read_b128 v[38:41], v246 offset:288
	ds_read_b128 v[54:57], v246 offset:416
	ds_read_b128 v[42:45], v246 offset:320
	ds_read_b128 v[58:61], v246 offset:448
	ds_read_b128 v[46:49], v246 offset:352
	ds_read_b128 v[62:65], v246 offset:480
	s_waitcnt lgkmcnt(1)
	v_mfma_f32_32x32x16_bf16 v[34:49], v[66:69], v[146:149], v[34:49]
	s_waitcnt lgkmcnt(0)
	v_mfma_f32_32x32x16_bf16 v[50:65], v[70:73], v[146:149], v[50:65]
	v_mfma_f32_32x32x16_bf16 v[34:49], v[74:77], v[150:153], v[34:49]
	v_mfma_f32_32x32x16_bf16 v[50:65], v[78:81], v[150:153], v[50:65]
	v_mfma_f32_32x32x16_bf16 v[34:49], v[82:85], v[154:157], v[34:49]
	v_mfma_f32_32x32x16_bf16 v[50:65], v[86:89], v[154:157], v[50:65]
	v_mfma_f32_32x32x16_bf16 v[34:49], v[90:93], v[158:161], v[34:49]
	v_mfma_f32_32x32x16_bf16 v[50:65], v[94:97], v[158:161], v[50:65]
	s_add_i32 s4, s58, 0x2000
	ds_read_b128 v[82:85], v247 offset:8192
	ds_read_b128 v[66:69], v246
	ds_read_b128 v[70:73], v246 offset:32
	ds_read_b128 v[74:77], v246 offset:64
	ds_read_b128 v[78:81], v246 offset:96
	s_nop 5
	v_exp_f32_e32 v162, v50
	v_exp_f32_e32 v138, v51
	v_exp_f32_e32 v130, v52
	s_waitcnt lgkmcnt(0)
	v_mfma_f32_32x32x16_bf16 v[66:81], v[82:85], v[146:149], v[66:81]
	ds_read_b128 v[82:85], v248 offset:8192
	ds_read_b128 v[86:89], v250 offset:8192
	v_exp_f32_e32 v122, v34
	v_exp_f32_e32 v134, v35
	v_exp_f32_e32 v126, v36
	v_exp_f32_e32 v116, v37
	s_waitcnt lgkmcnt(1)
	v_mfma_f32_32x32x16_bf16 v[66:81], v[82:85], v[150:153], v[66:81]
	ds_read_b128 v[82:85], v249 offset:8192
	ds_read_b128 v[34:37], v247 offset:12288
	ds_read_b128 v[90:93], v246 offset:192
	ds_read_b128 v[94:97], v246 offset:224
	v_exp_f32_e32 v172, v53
	v_exp_f32_e32 v186, v38
	v_exp_f32_e32 v168, v39
	s_waitcnt lgkmcnt(3)
	v_mfma_f32_32x32x16_bf16 v[66:81], v[82:85], v[154:157], v[66:81]
	ds_read_b128 v[82:85], v246 offset:128
	v_exp_f32_e32 v164, v40
	v_exp_f32_e32 v142, v41
	ds_read_b128 v[38:41], v250 offset:12288
	v_exp_f32_e32 v244, v54
	v_exp_f32_e32 v170, v55
	v_exp_f32_e32 v166, v56
	v_mfma_f32_32x32x16_bf16 v[66:81], v[86:89], v[158:161], v[66:81]
	ds_read_b128 v[86:89], v246 offset:160
	ds_read_b128 v[50:53], v248 offset:12288
	v_exp_f32_e32 v144, v57
	v_exp_f32_e32 v136, v42
	v_exp_f32_e32 v140, v58
	v_exp_f32_e32 v128, v43
	v_exp_f32_e32 v132, v59
	s_waitcnt lgkmcnt(1)
	v_mfma_f32_32x32x16_bf16 v[82:97], v[34:37], v[146:149], v[82:97]
	ds_read_b128 v[34:37], v249 offset:12288
	v_exp_f32_e32 v120, v44
	v_exp_f32_e32 v124, v60
	v_exp_f32_e32 v114, v45
	v_exp_f32_e32 v118, v61
	v_exp_f32_e32 v110, v46
	v_exp_f32_e32 v112, v62
	s_waitcnt lgkmcnt(1)
	v_mfma_f32_32x32x16_bf16 v[82:97], v[50:53], v[150:153], v[82:97]
	v_exp_f32_e32 v104, v47
	v_exp_f32_e32 v108, v63
	v_exp_f32_e32 v102, v48
	v_exp_f32_e32 v98, v49
	v_exp_f32_e32 v106, v64
	v_exp_f32_e32 v100, v65
	s_waitcnt lgkmcnt(0)
	v_mfma_f32_32x32x16_bf16 v[82:97], v[34:37], v[154:157], v[82:97]
	v_mfma_f32_32x32x16_bf16 v[82:97], v[38:41], v[158:161], v[82:97]
	v_cvt_pk_bf16_f32 v213, v126, v116
	v_cvt_pk_bf16_f32 v214, v186, v168
	v_cvt_pk_bf16_f32 v215, v164, v142
	v_cvt_pk_bf16_f32 v174, v136, v128
	v_cvt_pk_bf16_f32 v175, v120, v114
	v_cvt_pk_bf16_f32 v176, v110, v104
	v_cvt_pk_bf16_f32 v177, v102, v98
	v_cvt_pk_bf16_f32 v178, v162, v138
	v_cvt_pk_bf16_f32 v179, v130, v172
	v_cvt_pk_bf16_f32 v180, v244, v170
	v_cvt_pk_bf16_f32 v181, v166, v144
	v_cvt_pk_bf16_f32 v208, v140, v132
	v_cvt_pk_bf16_f32 v209, v124, v118
	v_cvt_pk_bf16_f32 v210, v112, v108
	v_cvt_pk_bf16_f32 v211, v106, v100
	v_cvt_pk_bf16_f32 v212, v122, v134
	ds_read_b64_tr_b16 v[50:51], v0 offset:16384
	ds_read_b64_tr_b16 v[52:53], v0 offset:16896
	ds_read_b64_tr_b16 v[216:217], v0 offset:20480
	ds_read_b64_tr_b16 v[218:219], v0 offset:20992
	v_exp_f32_e32 v123, v66
	v_exp_f32_e32 v163, v82
	v_exp_f32_e32 v135, v67
	v_exp_f32_e32 v139, v83
	v_exp_f32_e32 v127, v68
	v_exp_f32_e32 v187, v70
	v_exp_f32_e32 v245, v86
	v_exp_f32_e32 v131, v84
	v_exp_f32_e32 v117, v69
	v_exp_f32_e32 v173, v85
	v_exp_f32_e32 v169, v71
	v_exp_f32_e32 v165, v72
	v_exp_f32_e32 v143, v73
	v_exp_f32_e32 v137, v74
	v_exp_f32_e32 v129, v75
	v_exp_f32_e32 v121, v76
	v_exp_f32_e32 v115, v77
	v_exp_f32_e32 v111, v78
	v_exp_f32_e32 v105, v79
	v_exp_f32_e32 v103, v80
	v_exp_f32_e32 v99, v81
	ds_read_b64_tr_b16 v[220:221], v0 offset:17408
	ds_read_b64_tr_b16 v[222:223], v0 offset:17920
	ds_read_b64_tr_b16 v[224:225], v0 offset:21504
	ds_read_b64_tr_b16 v[226:227], v0 offset:22016
	ds_read_b64_tr_b16 v[228:229], v0 offset:18432
	ds_read_b64_tr_b16 v[230:231], v0 offset:18944
	ds_read_b64_tr_b16 v[232:233], v0 offset:22528
	ds_read_b64_tr_b16 v[234:235], v0 offset:23040
	ds_read_b64_tr_b16 v[236:237], v0 offset:19456
	ds_read_b64_tr_b16 v[238:239], v0 offset:19968
	ds_read_b64_tr_b16 v[240:241], v0 offset:23552
	ds_read_b64_tr_b16 v[242:243], v0 offset:24064
	s_waitcnt lgkmcnt(14)
	v_mfma_f32_32x32x16_bf16 v[18:33], v[212:215], v[50:53], v[18:33]
	v_add_f32_e64 v66, v186, v244
	v_add_f32_e64 v67, v187, v245
	v_cvt_pk_bf16_f32 v68, v123, v135
	v_cvt_pk_bf16_f32 v69, v127, v117
	v_cvt_pk_bf16_f32 v70, v187, v169
	v_cvt_pk_bf16_f32 v71, v165, v143
	v_cvt_pk_bf16_f32 v72, v137, v129
	v_cvt_pk_bf16_f32 v73, v121, v115
	v_cvt_pk_bf16_f32 v74, v111, v105
	v_cvt_pk_bf16_f32 v75, v103, v99
	v_cvt_pk_bf16_f32 v76, v163, v139
	v_cvt_pk_bf16_f32 v77, v131, v173
	s_waitcnt lgkmcnt(12)
	v_mfma_f32_32x32x16_bf16 v[2:17], v[212:215], v[216:219], v[2:17]
	v_exp_f32_e32 v171, v87
	v_exp_f32_e32 v167, v88
	v_exp_f32_e32 v145, v89
	v_exp_f32_e32 v141, v90
	v_exp_f32_e32 v133, v91
	v_exp_f32_e32 v125, v92
	v_exp_f32_e32 v119, v93
	v_exp_f32_e32 v113, v94
	v_exp_f32_e32 v109, v95
	v_exp_f32_e32 v107, v96
	v_exp_f32_e32 v101, v97
	v_cvt_pk_bf16_f32 v78, v245, v171
	v_cvt_pk_bf16_f32 v79, v167, v145
	v_cvt_pk_bf16_f32 v80, v141, v133
	v_cvt_pk_bf16_f32 v81, v125, v119
	v_cvt_pk_bf16_f32 v82, v113, v109
	v_cvt_pk_bf16_f32 v83, v107, v101
	s_waitcnt lgkmcnt(10)
	v_mfma_f32_32x32x16_bf16 v[18:33], v[174:177], v[220:223], v[18:33]
	v_add_f32_e64 v84, v122, v162
	v_add_f32_e64 v85, v123, v163
	v_add_f32_e64 v86, v134, v138
	v_add_f32_e64 v87, v135, v139
	v_add_f32_e64 v84, v84, 0
	v_add_f32_e64 v85, v85, 0
	v_pk_add_f32 v[88:89], v[126:127], v[130:131]
	v_pk_add_f32 v[84:85], v[86:87], v[84:85]
	v_pk_add_f32 v[90:91], v[116:117], v[172:173]
	v_pk_add_f32 v[84:85], v[88:89], v[84:85]
	s_waitcnt lgkmcnt(8)
	v_mfma_f32_32x32x16_bf16 v[2:17], v[174:177], v[224:227], v[2:17]
	v_add_f32_e64 v84, v90, v84
	v_add_f32_e64 v85, v91, v85
	v_add_f32_e64 v86, v168, v170
	v_add_f32_e64 v87, v169, v171
	v_add_f32_e64 v66, v66, v84
	v_add_f32_e64 v67, v67, v85
	v_pk_add_f32 v[88:89], v[164:165], v[166:167]
	v_pk_add_f32 v[66:67], v[86:87], v[66:67]
	v_pk_add_f32 v[90:91], v[142:143], v[144:145]
	v_pk_add_f32 v[66:67], v[88:89], v[66:67]
	s_waitcnt lgkmcnt(6)
	v_mfma_f32_32x32x16_bf16 v[18:33], v[178:181], v[228:231], v[18:33]
	v_add_f32_e64 v92, v136, v140
	v_add_f32_e64 v93, v137, v141
	v_add_f32_e64 v66, v90, v66
	v_add_f32_e64 v67, v91, v67
	v_add_f32_e64 v94, v128, v132
	v_add_f32_e64 v95, v129, v133
	v_pk_add_f32 v[66:67], v[92:93], v[66:67]
	v_pk_add_f32 v[96:97], v[120:121], v[124:125]
	v_pk_add_f32 v[66:67], v[94:95], v[66:67]
	v_pk_add_f32 v[114:115], v[114:115], v[118:119]
	s_waitcnt lgkmcnt(4)
	v_mfma_f32_32x32x16_bf16 v[2:17], v[178:181], v[232:235], v[2:17]
	v_add_f32_e64 v66, v96, v66
	v_add_f32_e64 v67, v97, v67
	v_add_f32_e64 v110, v110, v112
	v_add_f32_e64 v111, v111, v113
	v_add_f32_e64 v66, v114, v66
	v_add_f32_e64 v67, v115, v67
	v_pk_add_f32 v[104:105], v[104:105], v[108:109]
	v_pk_add_f32 v[66:67], v[110:111], v[66:67]
	v_pk_add_f32 v[102:103], v[102:103], v[106:107]
	v_pk_add_f32 v[66:67], v[104:105], v[66:67]
	s_waitcnt lgkmcnt(2)
	v_mfma_f32_32x32x16_bf16 v[18:33], v[208:211], v[236:239], v[18:33]
	v_add_f32_e64 v98, v98, v100
	v_add_f32_e64 v99, v99, v101
	v_add_f32_e64 v66, v102, v66
	v_add_f32_e64 v67, v103, v67
	v_add_f32_e64 v66, v98, v66
	v_add_f32_e64 v67, v99, v67
	v_add_f32_e32 v66, v205, v66
	s_waitcnt lgkmcnt(0)
	v_mfma_f32_32x32x16_bf16 v[2:17], v[208:211], v[240:243], v[2:17]
	v_add_f32_e32 v66, v66, v67
	ds_read_b64_tr_b16 v[84:85], v0 offset:24576
	ds_read_b64_tr_b16 v[86:87], v0 offset:25088
	ds_read_b64_tr_b16 v[88:89], v0 offset:25600
	ds_read_b64_tr_b16 v[90:91], v0 offset:26112
	s_waitcnt lgkmcnt(2)
	v_mfma_f32_32x32x16_bf16 v[18:33], v[68:71], v[84:87], v[18:33]
	ds_read_b64_tr_b16 v[84:85], v0 offset:28672
	ds_read_b64_tr_b16 v[86:87], v0 offset:29184
	ds_read_b64_tr_b16 v[92:93], v0 offset:29696
	ds_read_b64_tr_b16 v[94:95], v0 offset:30208
	s_waitcnt lgkmcnt(2)
	v_mfma_f32_32x32x16_bf16 v[2:17], v[68:71], v[84:87], v[2:17]
	ds_read_b64_tr_b16 v[68:69], v0 offset:26624
	ds_read_b64_tr_b16 v[70:71], v0 offset:27136
	ds_read_b64_tr_b16 v[84:85], v0 offset:31744
	ds_read_b64_tr_b16 v[86:87], v0 offset:32256
	v_mfma_f32_32x32x16_bf16 v[18:33], v[72:75], v[88:91], v[18:33]
	s_waitcnt lgkmcnt(4)
	v_mfma_f32_32x32x16_bf16 v[2:17], v[72:75], v[92:95], v[2:17]
	ds_read_b64_tr_b16 v[72:73], v0 offset:27648
	ds_read_b64_tr_b16 v[74:75], v0 offset:28160
	s_waitcnt lgkmcnt(4)
	v_mfma_f32_32x32x16_bf16 v[18:33], v[76:79], v[68:71], v[18:33]
	ds_read_b64_tr_b16 v[68:69], v0 offset:30720
	ds_read_b64_tr_b16 v[70:71], v0 offset:31232
	s_waitcnt lgkmcnt(0)
	v_mfma_f32_32x32x16_bf16 v[2:17], v[76:79], v[68:71], v[2:17]
	v_mfma_f32_32x32x16_bf16 v[18:33], v[80:83], v[72:75], v[18:33]
	v_mfma_f32_32x32x16_bf16 v[2:17], v[80:83], v[84:87], v[2:17]
	s_branch .LBB0_898

.LBB0_905:
	s_nop 7
	v_mov_b64_e32 v[50:51], v[2:3]
	v_mov_b64_e32 v[52:53], v[4:5]
	v_mov_b64_e32 v[54:55], v[6:7]
	v_mov_b64_e32 v[56:57], v[8:9]
	v_mov_b64_e32 v[58:59], v[10:11]
	v_mov_b64_e32 v[60:61], v[12:13]
	v_mov_b64_e32 v[62:63], v[14:15]
	v_mov_b64_e32 v[64:65], v[16:17]
	v_mov_b64_e32 v[34:35], v[18:19]
	v_mov_b64_e32 v[36:37], v[20:21]
	v_mov_b64_e32 v[38:39], v[22:23]
	v_mov_b64_e32 v[40:41], v[24:25]
	v_mov_b64_e32 v[42:43], v[26:27]
	v_mov_b64_e32 v[44:45], v[28:29]
	v_mov_b64_e32 v[46:47], v[30:31]
	v_mov_b64_e32 v[48:49], v[32:33]
	v_readlane_b32 s0, v253, 24
	s_and_b32 s0, s0, 0x3fffffc0
	s_setprio 0
	s_waitcnt vmcnt(0) lgkmcnt(0)
	s_barrier
	s_lshl_b32 s0, s0, 2
	s_add_i32 s2, s0, 0
	v_and_b32_e32 v0, 63, v193
	v_mov_b32_e32 v4, v205
	v_mov_b32_e32 v3, v205
	v_and_b32_e32 v2, 31, v193
	s_add_i32 s2, s2, 0x18000
	v_permlane32_swap_b32_e32 v4, v3
	v_cmp_gt_u32_e32 vcc, 32, v0
	s_and_saveexec_b64 s[0:1], vcc
	s_cbranch_execz .LBB0_855
	v_lshl_add_u32 v4, v2, 2, s2
	v_add_f32_e32 v3, v205, v3
	ds_write_b32 v4, v3 offset:128
	s_branch .LBB0_855
